# code placement: the 7 GEMM K-loop heads aligned to 64 bytes (.p2align 6), on top of v25
# speedup vs baseline: 1.0051x; 1.0051x over previous
.LBB0_130:
	s_ashr_i32 s17, s16, 31
	s_lshl_b64 s[24:25], s[16:17], 21
	s_add_u32 s24, s44, s24
	s_addc_u32 s25, s45, s25
	s_and_b64 s[26:27], s[22:23], exec
	s_cselect_b32 s7, s25, s35
	s_cselect_b32 s17, s24, s34
	s_ashr_i32 s21, s20, 31
	s_lshl_b64 s[26:27], s[20:21], 21
	s_add_u32 s26, s46, s26
	s_addc_u32 s27, s47, s27
	s_and_b64 s[36:37], s[22:23], exec
	s_cselect_b32 s21, s27, s31
	s_cselect_b32 s33, s26, s30
	s_add_u32 s55, s30, 0x100
	s_addc_u32 s56, s31, 0
	s_add_u32 s57, s34, 0x100
	v_mov_b32_e32 v6, 0
	s_addc_u32 s58, s35, 0
	s_mov_b32 s59, -2
	v_mov_b32_e32 v7, v6
	v_mov_b32_e32 v8, v6
	v_mov_b32_e32 v9, v6
	v_mov_b32_e32 v10, v6
	v_mov_b32_e32 v11, v6
	v_mov_b32_e32 v12, v6
	v_mov_b32_e32 v13, v6
	v_mov_b32_e32 v22, v6
	v_mov_b32_e32 v23, v6
	v_mov_b32_e32 v24, v6
	v_mov_b32_e32 v25, v6
	v_mov_b32_e32 v26, v6
	v_mov_b32_e32 v27, v6
	v_mov_b32_e32 v28, v6
	v_mov_b32_e32 v29, v6
	v_mov_b32_e32 v38, v6
	v_mov_b32_e32 v39, v6
	v_mov_b32_e32 v40, v6
	v_mov_b32_e32 v41, v6
	v_mov_b32_e32 v42, v6
	v_mov_b32_e32 v43, v6
	v_mov_b32_e32 v44, v6
	v_mov_b32_e32 v45, v6
	v_mov_b32_e32 v54, v6
	v_mov_b32_e32 v55, v6
	v_mov_b32_e32 v56, v6
	v_mov_b32_e32 v57, v6
	v_mov_b32_e32 v58, v6
	v_mov_b32_e32 v59, v6
	v_mov_b32_e32 v60, v6
	v_mov_b32_e32 v61, v6
	v_mov_b32_e32 v14, v6
	v_mov_b32_e32 v15, v6
	v_mov_b32_e32 v16, v6
	v_mov_b32_e32 v17, v6
	v_mov_b32_e32 v18, v6
	v_mov_b32_e32 v19, v6
	v_mov_b32_e32 v20, v6
	v_mov_b32_e32 v21, v6
	v_mov_b32_e32 v30, v6
	v_mov_b32_e32 v31, v6
	v_mov_b32_e32 v32, v6
	v_mov_b32_e32 v33, v6
	v_mov_b32_e32 v34, v6
	v_mov_b32_e32 v35, v6
	v_mov_b32_e32 v36, v6
	v_mov_b32_e32 v37, v6
	v_mov_b32_e32 v46, v6
	v_mov_b32_e32 v47, v6
	v_mov_b32_e32 v48, v6
	v_mov_b32_e32 v49, v6
	v_mov_b32_e32 v50, v6
	v_mov_b32_e32 v51, v6
	v_mov_b32_e32 v52, v6
	v_mov_b32_e32 v53, v6
	v_mov_b32_e32 v62, v6
	v_mov_b32_e32 v63, v6
	v_mov_b32_e32 v64, v6
	v_mov_b32_e32 v65, v6
	v_mov_b32_e32 v66, v6
	v_mov_b32_e32 v67, v6
	v_mov_b32_e32 v68, v6
	v_mov_b32_e32 v69, v6
	v_mov_b32_e32 v70, v6
	v_mov_b32_e32 v71, v6
	v_mov_b32_e32 v72, v6
	v_mov_b32_e32 v73, v6
	v_mov_b32_e32 v74, v6
	v_mov_b32_e32 v75, v6
	v_mov_b32_e32 v76, v6
	v_mov_b32_e32 v77, v6
	v_mov_b32_e32 v86, v6
	v_mov_b32_e32 v87, v6
	v_mov_b32_e32 v88, v6
	v_mov_b32_e32 v89, v6
	v_mov_b32_e32 v90, v6
	v_mov_b32_e32 v91, v6
	v_mov_b32_e32 v92, v6
	v_mov_b32_e32 v93, v6
	v_mov_b32_e32 v102, v6
	v_mov_b32_e32 v103, v6
	v_mov_b32_e32 v104, v6
	v_mov_b32_e32 v105, v6
	v_mov_b32_e32 v106, v6
	v_mov_b32_e32 v107, v6
	v_mov_b32_e32 v108, v6
	v_mov_b32_e32 v109, v6
	v_mov_b32_e32 v118, v6
	v_mov_b32_e32 v119, v6
	v_mov_b32_e32 v120, v6
	v_mov_b32_e32 v121, v6
	v_mov_b32_e32 v122, v6
	v_mov_b32_e32 v123, v6
	v_mov_b32_e32 v124, v6
	v_mov_b32_e32 v125, v6
	v_mov_b32_e32 v78, v6
	v_mov_b32_e32 v79, v6
	v_mov_b32_e32 v80, v6
	v_mov_b32_e32 v81, v6
	v_mov_b32_e32 v82, v6
	v_mov_b32_e32 v83, v6
	v_mov_b32_e32 v84, v6
	v_mov_b32_e32 v85, v6
	v_mov_b32_e32 v94, v6
	v_mov_b32_e32 v95, v6
	v_mov_b32_e32 v96, v6
	v_mov_b32_e32 v97, v6
	v_mov_b32_e32 v98, v6
	v_mov_b32_e32 v99, v6
	v_mov_b32_e32 v100, v6
	v_mov_b32_e32 v101, v6
	v_mov_b32_e32 v110, v6
	v_mov_b32_e32 v111, v6
	v_mov_b32_e32 v112, v6
	v_mov_b32_e32 v113, v6
	v_mov_b32_e32 v114, v6
	v_mov_b32_e32 v115, v6
	v_mov_b32_e32 v116, v6
	v_mov_b32_e32 v117, v6
	v_mov_b32_e32 v126, v6
	v_mov_b32_e32 v127, v6
	v_mov_b32_e32 v128, v6
	v_mov_b32_e32 v129, v6
	v_mov_b32_e32 v130, v6
	v_mov_b32_e32 v131, v6
	v_mov_b32_e32 v132, v6
	v_mov_b32_e32 v133, v6
	.p2align 6

.LBB0_250:
	s_ashr_i32 s11, s10, 31
	s_lshl_b64 s[16:17], s[10:11], 21
	s_add_u32 s16, s44, s16
	s_addc_u32 s17, s45, s17
	s_and_b64 s[20:21], s[28:29], exec
	s_cselect_b32 s1, s17, s27
	s_cselect_b32 s2, s16, s26
	s_ashr_i32 s15, s14, 31
	s_lshl_b64 s[20:21], s[14:15], 21
	s_add_u32 s20, s38, s20
	s_addc_u32 s21, s39, s21
	s_and_b64 s[28:29], s[28:29], exec
	s_cselect_b32 s11, s21, s25
	s_cselect_b32 s15, s20, s24
	s_add_u32 s19, s24, 0x100
	s_addc_u32 s33, s25, 0
	s_add_u32 s52, s26, 0x100
	v_mov_b32_e32 v118, 0
	s_addc_u32 s53, s27, 0
	s_mov_b32 s54, -2
	v_mov_b32_e32 v119, v118
	v_mov_b32_e32 v120, v118
	v_mov_b32_e32 v121, v118
	v_mov_b32_e32 v122, v118
	v_mov_b32_e32 v123, v118
	v_mov_b32_e32 v124, v118
	v_mov_b32_e32 v125, v118
	v_mov_b32_e32 v114, v118
	v_mov_b32_e32 v115, v118
	v_mov_b32_e32 v116, v118
	v_mov_b32_e32 v117, v118
	v_mov_b32_e32 v110, v118
	v_mov_b32_e32 v111, v118
	v_mov_b32_e32 v112, v118
	v_mov_b32_e32 v113, v118
	v_mov_b32_e32 v98, v118
	v_mov_b32_e32 v99, v118
	v_mov_b32_e32 v100, v118
	v_mov_b32_e32 v101, v118
	v_mov_b32_e32 v94, v118
	v_mov_b32_e32 v95, v118
	v_mov_b32_e32 v96, v118
	v_mov_b32_e32 v97, v118
	v_mov_b32_e32 v82, v118
	v_mov_b32_e32 v83, v118
	v_mov_b32_e32 v84, v118
	v_mov_b32_e32 v85, v118
	v_mov_b32_e32 v78, v118
	v_mov_b32_e32 v79, v118
	v_mov_b32_e32 v80, v118
	v_mov_b32_e32 v81, v118
	v_mov_b32_e32 v126, v118
	v_mov_b32_e32 v127, v118
	v_mov_b32_e32 v128, v118
	v_mov_b32_e32 v129, v118
	v_mov_b32_e32 v130, v118
	v_mov_b32_e32 v131, v118
	v_mov_b32_e32 v132, v118
	v_mov_b32_e32 v133, v118
	v_mov_b32_e32 v106, v118
	v_mov_b32_e32 v107, v118
	v_mov_b32_e32 v108, v118
	v_mov_b32_e32 v109, v118
	v_mov_b32_e32 v102, v118
	v_mov_b32_e32 v103, v118
	v_mov_b32_e32 v104, v118
	v_mov_b32_e32 v105, v118
	v_mov_b32_e32 v90, v118
	v_mov_b32_e32 v91, v118
	v_mov_b32_e32 v92, v118
	v_mov_b32_e32 v93, v118
	v_mov_b32_e32 v86, v118
	v_mov_b32_e32 v87, v118
	v_mov_b32_e32 v88, v118
	v_mov_b32_e32 v89, v118
	v_mov_b32_e32 v74, v118
	v_mov_b32_e32 v75, v118
	v_mov_b32_e32 v76, v118
	v_mov_b32_e32 v77, v118
	v_mov_b32_e32 v70, v118
	v_mov_b32_e32 v71, v118
	v_mov_b32_e32 v72, v118
	v_mov_b32_e32 v73, v118
	v_mov_b32_e32 v66, v118
	v_mov_b32_e32 v67, v118
	v_mov_b32_e32 v68, v118
	v_mov_b32_e32 v69, v118
	v_mov_b32_e32 v62, v118
	v_mov_b32_e32 v63, v118
	v_mov_b32_e32 v64, v118
	v_mov_b32_e32 v65, v118
	v_mov_b32_e32 v50, v118
	v_mov_b32_e32 v51, v118
	v_mov_b32_e32 v52, v118
	v_mov_b32_e32 v53, v118
	v_mov_b32_e32 v46, v118
	v_mov_b32_e32 v47, v118
	v_mov_b32_e32 v48, v118
	v_mov_b32_e32 v49, v118
	v_mov_b32_e32 v34, v118
	v_mov_b32_e32 v35, v118
	v_mov_b32_e32 v36, v118
	v_mov_b32_e32 v37, v118
	v_mov_b32_e32 v30, v118
	v_mov_b32_e32 v31, v118
	v_mov_b32_e32 v32, v118
	v_mov_b32_e32 v33, v118
	v_mov_b32_e32 v18, v118
	v_mov_b32_e32 v19, v118
	v_mov_b32_e32 v20, v118
	v_mov_b32_e32 v21, v118
	v_mov_b32_e32 v14, v118
	v_mov_b32_e32 v15, v118
	v_mov_b32_e32 v16, v118
	v_mov_b32_e32 v17, v118
	v_mov_b32_e32 v58, v118
	v_mov_b32_e32 v59, v118
	v_mov_b32_e32 v60, v118
	v_mov_b32_e32 v61, v118
	v_mov_b32_e32 v54, v118
	v_mov_b32_e32 v55, v118
	v_mov_b32_e32 v56, v118
	v_mov_b32_e32 v57, v118
	v_mov_b32_e32 v42, v118
	v_mov_b32_e32 v43, v118
	v_mov_b32_e32 v44, v118
	v_mov_b32_e32 v45, v118
	v_mov_b32_e32 v38, v118
	v_mov_b32_e32 v39, v118
	v_mov_b32_e32 v40, v118
	v_mov_b32_e32 v41, v118
	v_mov_b32_e32 v26, v118
	v_mov_b32_e32 v27, v118
	v_mov_b32_e32 v28, v118
	v_mov_b32_e32 v29, v118
	v_mov_b32_e32 v22, v118
	v_mov_b32_e32 v23, v118
	v_mov_b32_e32 v24, v118
	v_mov_b32_e32 v25, v118
	v_mov_b32_e32 v10, v118
	v_mov_b32_e32 v11, v118
	v_mov_b32_e32 v12, v118
	v_mov_b32_e32 v13, v118
	v_mov_b32_e32 v6, v118
	v_mov_b32_e32 v7, v118
	v_mov_b32_e32 v8, v118
	v_mov_b32_e32 v9, v118
	.p2align 6

.LBB0_345:
	s_ashr_i32 s11, s10, 31
	s_lshl_b64 s[16:17], s[10:11], 21
	s_add_u32 s16, s44, s16
	s_addc_u32 s17, s45, s17
	s_and_b64 s[20:21], s[28:29], exec
	s_cselect_b32 s1, s17, s27
	s_cselect_b32 s2, s16, s26
	s_ashr_i32 s15, s14, 31
	s_lshl_b64 s[20:21], s[14:15], 21
	s_add_u32 s20, s39, s20
	s_addc_u32 s21, s40, s21
	s_and_b64 s[28:29], s[28:29], exec
	s_cselect_b32 s11, s21, s25
	s_cselect_b32 s15, s20, s24
	s_add_u32 s19, s24, 0x100
	s_addc_u32 s23, s25, 0
	s_add_u32 s33, s26, 0x100
	v_mov_b32_e32 v6, 0
	s_addc_u32 s52, s27, 0
	s_mov_b32 s53, -2
	v_mov_b32_e32 v7, v6
	v_mov_b32_e32 v8, v6
	v_mov_b32_e32 v9, v6
	v_mov_b32_e32 v10, v6
	v_mov_b32_e32 v11, v6
	v_mov_b32_e32 v12, v6
	v_mov_b32_e32 v13, v6
	v_mov_b32_e32 v22, v6
	v_mov_b32_e32 v23, v6
	v_mov_b32_e32 v24, v6
	v_mov_b32_e32 v25, v6
	v_mov_b32_e32 v26, v6
	v_mov_b32_e32 v27, v6
	v_mov_b32_e32 v28, v6
	v_mov_b32_e32 v29, v6
	v_mov_b32_e32 v38, v6
	v_mov_b32_e32 v39, v6
	v_mov_b32_e32 v40, v6
	v_mov_b32_e32 v41, v6
	v_mov_b32_e32 v42, v6
	v_mov_b32_e32 v43, v6
	v_mov_b32_e32 v44, v6
	v_mov_b32_e32 v45, v6
	v_mov_b32_e32 v54, v6
	v_mov_b32_e32 v55, v6
	v_mov_b32_e32 v56, v6
	v_mov_b32_e32 v57, v6
	v_mov_b32_e32 v58, v6
	v_mov_b32_e32 v59, v6
	v_mov_b32_e32 v60, v6
	v_mov_b32_e32 v61, v6
	v_mov_b32_e32 v14, v6
	v_mov_b32_e32 v15, v6
	v_mov_b32_e32 v16, v6
	v_mov_b32_e32 v17, v6
	v_mov_b32_e32 v18, v6
	v_mov_b32_e32 v19, v6
	v_mov_b32_e32 v20, v6
	v_mov_b32_e32 v21, v6
	v_mov_b32_e32 v30, v6
	v_mov_b32_e32 v31, v6
	v_mov_b32_e32 v32, v6
	v_mov_b32_e32 v33, v6
	v_mov_b32_e32 v34, v6
	v_mov_b32_e32 v35, v6
	v_mov_b32_e32 v36, v6
	v_mov_b32_e32 v37, v6
	v_mov_b32_e32 v46, v6
	v_mov_b32_e32 v47, v6
	v_mov_b32_e32 v48, v6
	v_mov_b32_e32 v49, v6
	v_mov_b32_e32 v50, v6
	v_mov_b32_e32 v51, v6
	v_mov_b32_e32 v52, v6
	v_mov_b32_e32 v53, v6
	v_mov_b32_e32 v62, v6
	v_mov_b32_e32 v63, v6
	v_mov_b32_e32 v64, v6
	v_mov_b32_e32 v65, v6
	v_mov_b32_e32 v66, v6
	v_mov_b32_e32 v67, v6
	v_mov_b32_e32 v68, v6
	v_mov_b32_e32 v69, v6
	v_mov_b32_e32 v70, v6
	v_mov_b32_e32 v71, v6
	v_mov_b32_e32 v72, v6
	v_mov_b32_e32 v73, v6
	v_mov_b32_e32 v74, v6
	v_mov_b32_e32 v75, v6
	v_mov_b32_e32 v76, v6
	v_mov_b32_e32 v77, v6
	v_mov_b32_e32 v86, v6
	v_mov_b32_e32 v87, v6
	v_mov_b32_e32 v88, v6
	v_mov_b32_e32 v89, v6
	v_mov_b32_e32 v90, v6
	v_mov_b32_e32 v91, v6
	v_mov_b32_e32 v92, v6
	v_mov_b32_e32 v93, v6
	v_mov_b32_e32 v102, v6
	v_mov_b32_e32 v103, v6
	v_mov_b32_e32 v104, v6
	v_mov_b32_e32 v105, v6
	v_mov_b32_e32 v106, v6
	v_mov_b32_e32 v107, v6
	v_mov_b32_e32 v108, v6
	v_mov_b32_e32 v109, v6
	v_mov_b32_e32 v118, v6
	v_mov_b32_e32 v119, v6
	v_mov_b32_e32 v120, v6
	v_mov_b32_e32 v121, v6
	v_mov_b32_e32 v122, v6
	v_mov_b32_e32 v123, v6
	v_mov_b32_e32 v124, v6
	v_mov_b32_e32 v125, v6
	v_mov_b32_e32 v78, v6
	v_mov_b32_e32 v79, v6
	v_mov_b32_e32 v80, v6
	v_mov_b32_e32 v81, v6
	v_mov_b32_e32 v82, v6
	v_mov_b32_e32 v83, v6
	v_mov_b32_e32 v84, v6
	v_mov_b32_e32 v85, v6
	v_mov_b32_e32 v94, v6
	v_mov_b32_e32 v95, v6
	v_mov_b32_e32 v96, v6
	v_mov_b32_e32 v97, v6
	v_mov_b32_e32 v98, v6
	v_mov_b32_e32 v99, v6
	v_mov_b32_e32 v100, v6
	v_mov_b32_e32 v101, v6
	v_mov_b32_e32 v110, v6
	v_mov_b32_e32 v111, v6
	v_mov_b32_e32 v112, v6
	v_mov_b32_e32 v113, v6
	v_mov_b32_e32 v114, v6
	v_mov_b32_e32 v115, v6
	v_mov_b32_e32 v116, v6
	v_mov_b32_e32 v117, v6
	v_mov_b32_e32 v126, v6
	v_mov_b32_e32 v127, v6
	v_mov_b32_e32 v128, v6
	v_mov_b32_e32 v129, v6
	v_mov_b32_e32 v130, v6
	v_mov_b32_e32 v131, v6
	v_mov_b32_e32 v132, v6
	v_mov_b32_e32 v133, v6
	.p2align 6

.LBB0_453:
	s_ashr_i32 s21, s20, 31
	s_lshl_b64 s[24:25], s[20:21], 19
	s_add_u32 s24, s47, s24
	s_addc_u32 s25, s48, s25
	s_and_b64 s[26:27], s[16:17], exec
	s_cselect_b32 s3, s25, s37
	s_cselect_b32 s21, s24, s36
	s_ashr_i32 s23, s22, 31
	s_lshl_b64 s[26:27], s[22:23], 19
	s_add_u32 s26, s49, s26
	s_addc_u32 s27, s50, s27
	s_and_b64 s[38:39], s[16:17], exec
	s_cselect_b32 s23, s27, s35
	s_cselect_b32 s31, s26, s34
	s_add_u32 s33, s34, 0x100
	s_addc_u32 s61, s35, 0
	s_add_u32 s62, s36, 0x100
	v_mov_b32_e32 v6, 0
	s_addc_u32 s63, s37, 0
	s_mov_b32 s64, -2
	v_mov_b32_e32 v7, v6
	v_mov_b32_e32 v8, v6
	v_mov_b32_e32 v9, v6
	v_mov_b32_e32 v10, v6
	v_mov_b32_e32 v11, v6
	v_mov_b32_e32 v12, v6
	v_mov_b32_e32 v13, v6
	v_mov_b32_e32 v22, v6
	v_mov_b32_e32 v23, v6
	v_mov_b32_e32 v24, v6
	v_mov_b32_e32 v25, v6
	v_mov_b32_e32 v26, v6
	v_mov_b32_e32 v27, v6
	v_mov_b32_e32 v28, v6
	v_mov_b32_e32 v29, v6
	v_mov_b32_e32 v38, v6
	v_mov_b32_e32 v39, v6
	v_mov_b32_e32 v40, v6
	v_mov_b32_e32 v41, v6
	v_mov_b32_e32 v42, v6
	v_mov_b32_e32 v43, v6
	v_mov_b32_e32 v44, v6
	v_mov_b32_e32 v45, v6
	v_mov_b32_e32 v54, v6
	v_mov_b32_e32 v55, v6
	v_mov_b32_e32 v56, v6
	v_mov_b32_e32 v57, v6
	v_mov_b32_e32 v58, v6
	v_mov_b32_e32 v59, v6
	v_mov_b32_e32 v60, v6
	v_mov_b32_e32 v61, v6
	v_mov_b32_e32 v14, v6
	v_mov_b32_e32 v15, v6
	v_mov_b32_e32 v16, v6
	v_mov_b32_e32 v17, v6
	v_mov_b32_e32 v18, v6
	v_mov_b32_e32 v19, v6
	v_mov_b32_e32 v20, v6
	v_mov_b32_e32 v21, v6
	v_mov_b32_e32 v30, v6
	v_mov_b32_e32 v31, v6
	v_mov_b32_e32 v32, v6
	v_mov_b32_e32 v33, v6
	v_mov_b32_e32 v34, v6
	v_mov_b32_e32 v35, v6
	v_mov_b32_e32 v36, v6
	v_mov_b32_e32 v37, v6
	v_mov_b32_e32 v46, v6
	v_mov_b32_e32 v47, v6
	v_mov_b32_e32 v48, v6
	v_mov_b32_e32 v49, v6
	v_mov_b32_e32 v50, v6
	v_mov_b32_e32 v51, v6
	v_mov_b32_e32 v52, v6
	v_mov_b32_e32 v53, v6
	v_mov_b32_e32 v62, v6
	v_mov_b32_e32 v63, v6
	v_mov_b32_e32 v64, v6
	v_mov_b32_e32 v65, v6
	v_mov_b32_e32 v66, v6
	v_mov_b32_e32 v67, v6
	v_mov_b32_e32 v68, v6
	v_mov_b32_e32 v69, v6
	v_mov_b32_e32 v70, v6
	v_mov_b32_e32 v71, v6
	v_mov_b32_e32 v72, v6
	v_mov_b32_e32 v73, v6
	v_mov_b32_e32 v74, v6
	v_mov_b32_e32 v75, v6
	v_mov_b32_e32 v76, v6
	v_mov_b32_e32 v77, v6
	v_mov_b32_e32 v86, v6
	v_mov_b32_e32 v87, v6
	v_mov_b32_e32 v88, v6
	v_mov_b32_e32 v89, v6
	v_mov_b32_e32 v90, v6
	v_mov_b32_e32 v91, v6
	v_mov_b32_e32 v92, v6
	v_mov_b32_e32 v93, v6
	v_mov_b32_e32 v102, v6
	v_mov_b32_e32 v103, v6
	v_mov_b32_e32 v104, v6
	v_mov_b32_e32 v105, v6
	v_mov_b32_e32 v106, v6
	v_mov_b32_e32 v107, v6
	v_mov_b32_e32 v108, v6
	v_mov_b32_e32 v109, v6
	v_mov_b32_e32 v118, v6
	v_mov_b32_e32 v119, v6
	v_mov_b32_e32 v120, v6
	v_mov_b32_e32 v121, v6
	v_mov_b32_e32 v122, v6
	v_mov_b32_e32 v123, v6
	v_mov_b32_e32 v124, v6
	v_mov_b32_e32 v125, v6
	v_mov_b32_e32 v78, v6
	v_mov_b32_e32 v79, v6
	v_mov_b32_e32 v80, v6
	v_mov_b32_e32 v81, v6
	v_mov_b32_e32 v82, v6
	v_mov_b32_e32 v83, v6
	v_mov_b32_e32 v84, v6
	v_mov_b32_e32 v85, v6
	v_mov_b32_e32 v94, v6
	v_mov_b32_e32 v95, v6
	v_mov_b32_e32 v96, v6
	v_mov_b32_e32 v97, v6
	v_mov_b32_e32 v98, v6
	v_mov_b32_e32 v99, v6
	v_mov_b32_e32 v100, v6
	v_mov_b32_e32 v101, v6
	v_mov_b32_e32 v110, v6
	v_mov_b32_e32 v111, v6
	v_mov_b32_e32 v112, v6
	v_mov_b32_e32 v113, v6
	v_mov_b32_e32 v114, v6
	v_mov_b32_e32 v115, v6
	v_mov_b32_e32 v116, v6
	v_mov_b32_e32 v117, v6
	v_mov_b32_e32 v126, v6
	v_mov_b32_e32 v127, v6
	v_mov_b32_e32 v128, v6
	v_mov_b32_e32 v129, v6
	v_mov_b32_e32 v130, v6
	v_mov_b32_e32 v131, v6
	v_mov_b32_e32 v132, v6
	v_mov_b32_e32 v133, v6
	.p2align 6

.LBB0_479:
	s_ashr_i32 s15, s14, 31
	s_lshl_b64 s[20:21], s[14:15], 18
	s_add_u32 s20, s3, s20
	s_addc_u32 s21, s38, s21
	s_and_b64 s[22:23], s[18:19], exec
	s_cselect_b32 s15, s21, s29
	s_cselect_b32 s25, s20, s28
	s_ashr_i32 s17, s16, 31
	s_lshl_b64 s[22:23], s[16:17], 18
	s_add_u32 s22, s36, s22
	s_addc_u32 s23, s37, s23
	s_and_b64 s[30:31], s[18:19], exec
	s_cselect_b32 s17, s23, s27
	s_cselect_b32 s33, s22, s26
	s_add_u32 s52, s26, 0x100
	s_addc_u32 s53, s27, 0
	s_add_u32 s54, s28, 0x100
	v_mov_b32_e32 v6, 0
	s_addc_u32 s55, s29, 0
	s_mov_b32 s56, -2
	v_mov_b32_e32 v7, v6
	v_mov_b32_e32 v8, v6
	v_mov_b32_e32 v9, v6
	v_mov_b32_e32 v10, v6
	v_mov_b32_e32 v11, v6
	v_mov_b32_e32 v12, v6
	v_mov_b32_e32 v13, v6
	v_mov_b32_e32 v22, v6
	v_mov_b32_e32 v23, v6
	v_mov_b32_e32 v24, v6
	v_mov_b32_e32 v25, v6
	v_mov_b32_e32 v26, v6
	v_mov_b32_e32 v27, v6
	v_mov_b32_e32 v28, v6
	v_mov_b32_e32 v29, v6
	v_mov_b32_e32 v38, v6
	v_mov_b32_e32 v39, v6
	v_mov_b32_e32 v40, v6
	v_mov_b32_e32 v41, v6
	v_mov_b32_e32 v42, v6
	v_mov_b32_e32 v43, v6
	v_mov_b32_e32 v44, v6
	v_mov_b32_e32 v45, v6
	v_mov_b32_e32 v54, v6
	v_mov_b32_e32 v55, v6
	v_mov_b32_e32 v56, v6
	v_mov_b32_e32 v57, v6
	v_mov_b32_e32 v58, v6
	v_mov_b32_e32 v59, v6
	v_mov_b32_e32 v60, v6
	v_mov_b32_e32 v61, v6
	v_mov_b32_e32 v14, v6
	v_mov_b32_e32 v15, v6
	v_mov_b32_e32 v16, v6
	v_mov_b32_e32 v17, v6
	v_mov_b32_e32 v18, v6
	v_mov_b32_e32 v19, v6
	v_mov_b32_e32 v20, v6
	v_mov_b32_e32 v21, v6
	v_mov_b32_e32 v30, v6
	v_mov_b32_e32 v31, v6
	v_mov_b32_e32 v32, v6
	v_mov_b32_e32 v33, v6
	v_mov_b32_e32 v34, v6
	v_mov_b32_e32 v35, v6
	v_mov_b32_e32 v36, v6
	v_mov_b32_e32 v37, v6
	v_mov_b32_e32 v46, v6
	v_mov_b32_e32 v47, v6
	v_mov_b32_e32 v48, v6
	v_mov_b32_e32 v49, v6
	v_mov_b32_e32 v50, v6
	v_mov_b32_e32 v51, v6
	v_mov_b32_e32 v52, v6
	v_mov_b32_e32 v53, v6
	v_mov_b32_e32 v62, v6
	v_mov_b32_e32 v63, v6
	v_mov_b32_e32 v64, v6
	v_mov_b32_e32 v65, v6
	v_mov_b32_e32 v66, v6
	v_mov_b32_e32 v67, v6
	v_mov_b32_e32 v68, v6
	v_mov_b32_e32 v69, v6
	v_mov_b32_e32 v70, v6
	v_mov_b32_e32 v71, v6
	v_mov_b32_e32 v72, v6
	v_mov_b32_e32 v73, v6
	v_mov_b32_e32 v74, v6
	v_mov_b32_e32 v75, v6
	v_mov_b32_e32 v76, v6
	v_mov_b32_e32 v77, v6
	v_mov_b32_e32 v86, v6
	v_mov_b32_e32 v87, v6
	v_mov_b32_e32 v88, v6
	v_mov_b32_e32 v89, v6
	v_mov_b32_e32 v90, v6
	v_mov_b32_e32 v91, v6
	v_mov_b32_e32 v92, v6
	v_mov_b32_e32 v93, v6
	v_mov_b32_e32 v102, v6
	v_mov_b32_e32 v103, v6
	v_mov_b32_e32 v104, v6
	v_mov_b32_e32 v105, v6
	v_mov_b32_e32 v106, v6
	v_mov_b32_e32 v107, v6
	v_mov_b32_e32 v108, v6
	v_mov_b32_e32 v109, v6
	v_mov_b32_e32 v118, v6
	v_mov_b32_e32 v119, v6
	v_mov_b32_e32 v120, v6
	v_mov_b32_e32 v121, v6
	v_mov_b32_e32 v122, v6
	v_mov_b32_e32 v123, v6
	v_mov_b32_e32 v124, v6
	v_mov_b32_e32 v125, v6
	v_mov_b32_e32 v78, v6
	v_mov_b32_e32 v79, v6
	v_mov_b32_e32 v80, v6
	v_mov_b32_e32 v81, v6
	v_mov_b32_e32 v82, v6
	v_mov_b32_e32 v83, v6
	v_mov_b32_e32 v84, v6
	v_mov_b32_e32 v85, v6
	v_mov_b32_e32 v94, v6
	v_mov_b32_e32 v95, v6
	v_mov_b32_e32 v96, v6
	v_mov_b32_e32 v97, v6
	v_mov_b32_e32 v98, v6
	v_mov_b32_e32 v99, v6
	v_mov_b32_e32 v100, v6
	v_mov_b32_e32 v101, v6
	v_mov_b32_e32 v110, v6
	v_mov_b32_e32 v111, v6
	v_mov_b32_e32 v112, v6
	v_mov_b32_e32 v113, v6
	v_mov_b32_e32 v114, v6
	v_mov_b32_e32 v115, v6
	v_mov_b32_e32 v116, v6
	v_mov_b32_e32 v117, v6
	v_mov_b32_e32 v126, v6
	v_mov_b32_e32 v127, v6
	v_mov_b32_e32 v128, v6
	v_mov_b32_e32 v129, v6
	v_mov_b32_e32 v130, v6
	v_mov_b32_e32 v131, v6
	v_mov_b32_e32 v132, v6
	v_mov_b32_e32 v133, v6
	.p2align 6

.LBB0_535:
	s_ashr_i32 s7, s6, 31
	s_lshl_b64 s[10:11], s[6:7], 18
	s_add_u32 s10, s3, s10
	s_addc_u32 s11, s30, s11
	s_and_b64 s[12:13], s[22:23], exec
	s_cselect_b32 s7, s11, s21
	s_cselect_b32 s41, s10, s20
	s_ashr_i32 s9, s8, 31
	s_lshl_b64 s[12:13], s[8:9], 18
	s_add_u32 s12, s36, s12
	s_addc_u32 s13, s37, s13
	s_and_b64 s[22:23], s[22:23], exec
	s_cselect_b32 s9, s13, s19
	s_cselect_b32 s42, s12, s18
	s_add_u32 s43, s18, 0x100
	s_addc_u32 s44, s19, 0
	s_add_u32 s45, s20, 0x100
	v_mov_b32_e32 v6, 0
	s_addc_u32 s46, s21, 0
	s_mov_b32 s47, -2
	v_mov_b32_e32 v7, v6
	v_mov_b32_e32 v8, v6
	v_mov_b32_e32 v9, v6
	v_mov_b32_e32 v10, v6
	v_mov_b32_e32 v11, v6
	v_mov_b32_e32 v12, v6
	v_mov_b32_e32 v13, v6
	v_mov_b32_e32 v14, v6
	v_mov_b32_e32 v15, v6
	v_mov_b32_e32 v16, v6
	v_mov_b32_e32 v17, v6
	v_mov_b32_e32 v22, v6
	v_mov_b32_e32 v23, v6
	v_mov_b32_e32 v24, v6
	v_mov_b32_e32 v25, v6
	v_mov_b32_e32 v30, v6
	v_mov_b32_e32 v31, v6
	v_mov_b32_e32 v32, v6
	v_mov_b32_e32 v33, v6
	v_mov_b32_e32 v38, v6
	v_mov_b32_e32 v39, v6
	v_mov_b32_e32 v40, v6
	v_mov_b32_e32 v41, v6
	v_mov_b32_e32 v46, v6
	v_mov_b32_e32 v47, v6
	v_mov_b32_e32 v48, v6
	v_mov_b32_e32 v49, v6
	v_mov_b32_e32 v54, v6
	v_mov_b32_e32 v55, v6
	v_mov_b32_e32 v56, v6
	v_mov_b32_e32 v57, v6
	v_mov_b32_e32 v18, v6
	v_mov_b32_e32 v19, v6
	v_mov_b32_e32 v20, v6
	v_mov_b32_e32 v21, v6
	v_mov_b32_e32 v26, v6
	v_mov_b32_e32 v27, v6
	v_mov_b32_e32 v28, v6
	v_mov_b32_e32 v29, v6
	v_mov_b32_e32 v34, v6
	v_mov_b32_e32 v35, v6
	v_mov_b32_e32 v36, v6
	v_mov_b32_e32 v37, v6
	v_mov_b32_e32 v42, v6
	v_mov_b32_e32 v43, v6
	v_mov_b32_e32 v44, v6
	v_mov_b32_e32 v45, v6
	v_mov_b32_e32 v50, v6
	v_mov_b32_e32 v51, v6
	v_mov_b32_e32 v52, v6
	v_mov_b32_e32 v53, v6
	v_mov_b32_e32 v58, v6
	v_mov_b32_e32 v59, v6
	v_mov_b32_e32 v60, v6
	v_mov_b32_e32 v61, v6
	v_mov_b32_e32 v62, v6
	v_mov_b32_e32 v63, v6
	v_mov_b32_e32 v64, v6
	v_mov_b32_e32 v65, v6
	v_mov_b32_e32 v66, v6
	v_mov_b32_e32 v67, v6
	v_mov_b32_e32 v68, v6
	v_mov_b32_e32 v69, v6
	v_mov_b32_e32 v70, v6
	v_mov_b32_e32 v71, v6
	v_mov_b32_e32 v72, v6
	v_mov_b32_e32 v73, v6
	v_mov_b32_e32 v74, v6
	v_mov_b32_e32 v75, v6
	v_mov_b32_e32 v76, v6
	v_mov_b32_e32 v77, v6
	v_mov_b32_e32 v78, v6
	v_mov_b32_e32 v79, v6
	v_mov_b32_e32 v80, v6
	v_mov_b32_e32 v81, v6
	v_mov_b32_e32 v86, v6
	v_mov_b32_e32 v87, v6
	v_mov_b32_e32 v88, v6
	v_mov_b32_e32 v89, v6
	v_mov_b32_e32 v94, v6
	v_mov_b32_e32 v95, v6
	v_mov_b32_e32 v96, v6
	v_mov_b32_e32 v97, v6
	v_mov_b32_e32 v102, v6
	v_mov_b32_e32 v103, v6
	v_mov_b32_e32 v104, v6
	v_mov_b32_e32 v105, v6
	v_mov_b32_e32 v110, v6
	v_mov_b32_e32 v111, v6
	v_mov_b32_e32 v112, v6
	v_mov_b32_e32 v113, v6
	v_mov_b32_e32 v118, v6
	v_mov_b32_e32 v119, v6
	v_mov_b32_e32 v120, v6
	v_mov_b32_e32 v121, v6
	v_mov_b32_e32 v82, v6
	v_mov_b32_e32 v83, v6
	v_mov_b32_e32 v84, v6
	v_mov_b32_e32 v85, v6
	v_mov_b32_e32 v90, v6
	v_mov_b32_e32 v91, v6
	v_mov_b32_e32 v92, v6
	v_mov_b32_e32 v93, v6
	v_mov_b32_e32 v98, v6
	v_mov_b32_e32 v99, v6
	v_mov_b32_e32 v100, v6
	v_mov_b32_e32 v101, v6
	v_mov_b32_e32 v106, v6
	v_mov_b32_e32 v107, v6
	v_mov_b32_e32 v108, v6
	v_mov_b32_e32 v109, v6
	v_mov_b32_e32 v114, v6
	v_mov_b32_e32 v115, v6
	v_mov_b32_e32 v116, v6
	v_mov_b32_e32 v117, v6
	v_mov_b32_e32 v122, v6
	v_mov_b32_e32 v123, v6
	v_mov_b32_e32 v124, v6
	v_mov_b32_e32 v125, v6
	v_mov_b32_e32 v126, v6
	v_mov_b32_e32 v127, v6
	v_mov_b32_e32 v128, v6
	v_mov_b32_e32 v129, v6
	v_mov_b32_e32 v130, v6
	v_mov_b32_e32 v131, v6
	v_mov_b32_e32 v132, v6
	v_mov_b32_e32 v133, v6
	.p2align 6

.LBB0_923:
	s_ashr_i32 s11, s10, 31
	s_lshl_b64 s[14:15], s[10:11], 21
	s_add_u32 s14, s31, s14
	s_addc_u32 s15, s34, s15
	s_and_b64 s[16:17], s[22:23], exec
	s_cselect_b32 s7, s15, s21
	s_cselect_b32 s9, s14, s20
	s_ashr_i32 s13, s12, 31
	s_lshl_b64 s[16:17], s[12:13], 21
	s_add_u32 s16, s3, s16
	s_addc_u32 s17, s30, s17
	s_and_b64 s[22:23], s[22:23], exec
	s_cselect_b32 s11, s17, s19
	s_cselect_b32 s13, s16, s18
	s_add_u32 s33, s18, 0x100
	s_addc_u32 s44, s19, 0
	s_add_u32 s45, s20, 0x100
	v_mov_b32_e32 v6, 0
	s_addc_u32 s46, s21, 0
	s_mov_b32 s47, -2
	v_mov_b32_e32 v7, v6
	v_mov_b32_e32 v8, v6
	v_mov_b32_e32 v9, v6
	v_mov_b32_e32 v10, v6
	v_mov_b32_e32 v11, v6
	v_mov_b32_e32 v12, v6
	v_mov_b32_e32 v13, v6
	v_mov_b32_e32 v18, v6
	v_mov_b32_e32 v19, v6
	v_mov_b32_e32 v20, v6
	v_mov_b32_e32 v21, v6
	v_mov_b32_e32 v26, v6
	v_mov_b32_e32 v27, v6
	v_mov_b32_e32 v28, v6
	v_mov_b32_e32 v29, v6
	v_mov_b32_e32 v34, v6
	v_mov_b32_e32 v35, v6
	v_mov_b32_e32 v36, v6
	v_mov_b32_e32 v37, v6
	v_mov_b32_e32 v42, v6
	v_mov_b32_e32 v43, v6
	v_mov_b32_e32 v44, v6
	v_mov_b32_e32 v45, v6
	v_mov_b32_e32 v50, v6
	v_mov_b32_e32 v51, v6
	v_mov_b32_e32 v52, v6
	v_mov_b32_e32 v53, v6
	v_mov_b32_e32 v58, v6
	v_mov_b32_e32 v59, v6
	v_mov_b32_e32 v60, v6
	v_mov_b32_e32 v61, v6
	v_mov_b32_e32 v14, v6
	v_mov_b32_e32 v15, v6
	v_mov_b32_e32 v16, v6
	v_mov_b32_e32 v17, v6
	v_mov_b32_e32 v22, v6
	v_mov_b32_e32 v23, v6
	v_mov_b32_e32 v24, v6
	v_mov_b32_e32 v25, v6
	v_mov_b32_e32 v30, v6
	v_mov_b32_e32 v31, v6
	v_mov_b32_e32 v32, v6
	v_mov_b32_e32 v33, v6
	v_mov_b32_e32 v38, v6
	v_mov_b32_e32 v39, v6
	v_mov_b32_e32 v40, v6
	v_mov_b32_e32 v41, v6
	v_mov_b32_e32 v46, v6
	v_mov_b32_e32 v47, v6
	v_mov_b32_e32 v48, v6
	v_mov_b32_e32 v49, v6
	v_mov_b32_e32 v54, v6
	v_mov_b32_e32 v55, v6
	v_mov_b32_e32 v56, v6
	v_mov_b32_e32 v57, v6
	v_mov_b32_e32 v62, v6
	v_mov_b32_e32 v63, v6
	v_mov_b32_e32 v64, v6
	v_mov_b32_e32 v65, v6
	v_mov_b32_e32 v66, v6
	v_mov_b32_e32 v67, v6
	v_mov_b32_e32 v68, v6
	v_mov_b32_e32 v69, v6
	v_mov_b32_e32 v70, v6
	v_mov_b32_e32 v71, v6
	v_mov_b32_e32 v72, v6
	v_mov_b32_e32 v73, v6
	v_mov_b32_e32 v74, v6
	v_mov_b32_e32 v75, v6
	v_mov_b32_e32 v76, v6
	v_mov_b32_e32 v77, v6
	v_mov_b32_e32 v98, v6
	v_mov_b32_e32 v99, v6
	v_mov_b32_e32 v100, v6
	v_mov_b32_e32 v101, v6
	v_mov_b32_e32 v106, v6
	v_mov_b32_e32 v107, v6
	v_mov_b32_e32 v108, v6
	v_mov_b32_e32 v109, v6
	v_mov_b32_e32 v114, v6
	v_mov_b32_e32 v115, v6
	v_mov_b32_e32 v116, v6
	v_mov_b32_e32 v117, v6
	v_mov_b32_e32 v122, v6
	v_mov_b32_e32 v123, v6
	v_mov_b32_e32 v124, v6
	v_mov_b32_e32 v125, v6
	v_mov_b32_e32 v130, v6
	v_mov_b32_e32 v131, v6
	v_mov_b32_e32 v132, v6
	v_mov_b32_e32 v133, v6
	v_mov_b32_e32 v138, v6
	v_mov_b32_e32 v139, v6
	v_mov_b32_e32 v140, v6
	v_mov_b32_e32 v141, v6
	v_mov_b32_e32 v94, v6
	v_mov_b32_e32 v95, v6
	v_mov_b32_e32 v96, v6
	v_mov_b32_e32 v97, v6
	v_mov_b32_e32 v102, v6
	v_mov_b32_e32 v103, v6
	v_mov_b32_e32 v104, v6
	v_mov_b32_e32 v105, v6
	v_mov_b32_e32 v110, v6
	v_mov_b32_e32 v111, v6
	v_mov_b32_e32 v112, v6
	v_mov_b32_e32 v113, v6
	v_mov_b32_e32 v118, v6
	v_mov_b32_e32 v119, v6
	v_mov_b32_e32 v120, v6
	v_mov_b32_e32 v121, v6
	v_mov_b32_e32 v126, v6
	v_mov_b32_e32 v127, v6
	v_mov_b32_e32 v128, v6
	v_mov_b32_e32 v129, v6
	v_mov_b32_e32 v134, v6
	v_mov_b32_e32 v135, v6
	v_mov_b32_e32 v136, v6
	v_mov_b32_e32 v137, v6
	v_mov_b32_e32 v150, v6
	v_mov_b32_e32 v151, v6
	v_mov_b32_e32 v152, v6
	v_mov_b32_e32 v153, v6
	v_mov_b32_e32 v154, v6
	v_mov_b32_e32 v155, v6
	v_mov_b32_e32 v156, v6
	v_mov_b32_e32 v157, v6
	.p2align 6
